# speedup vs baseline: 1.0056x; 1.0004x over previous
; template <int RG, int NSW>
; __device__ __forceinline__ void scan_job(const Params& p, float* lds, const size_t tok0, const int T, const int head,
;                                          const int dir, const int row_base, const int rk_sel) {
;     ...
;     if (wave < 4) scan_waves<RG, NSW>(p, lds, T, dir, wave, lane, tok0, head, row_base);
;     else if (wave == 4) prep_waves<1, true, 0>(p, lds, T, dir, lane, tok0, head, 0, rk_sel);
;     else if (wave == 5) prep_waves<3, true, 1>(p, lds, T, dir, lane, tok0, head, 1, rk_sel);
;     else prep_waves<6, false, 0>(p, lds, T, dir, lane, tok0, head, 4 + (wave - 6) * 6, rk_sel);
; __device__ __forceinline__ void phase_scan(const Params& p, float* lds) {
;     ...
;       for (int i = 0; i < 4; ++i) scan_run_job(p, lds, 128 + c0 + i * 128);
.LBB0_1117:
	s_setprio 0
	s_or_b64 exec, exec, s[6:7]
	s_add_i32 s89, s89, 1
	s_cmp_eq_u32 s89, 4
	s_cbranch_scc1 .LBB0_1225

; template <int RG, int NSW>
; __device__ __forceinline__ void scan_waves(const Params& p, float* lds, const int T, const int dir, const int wave, const int lane,
;                                            const size_t tok0, const int head, const int row_base) {
;     ...
;   const int rowl = lane >> 3, part = lane & 7, k0 = part * 8;
;   int rowi[RG]; f32x2_t S[RG][4];
; #pragma unroll
;   for (int g = 0; g < RG; ++g) {
;     rowi[g] = row_base + g * (NSW * 8) + wave * 8 + rowl;
; #pragma unroll
;     for (int k = 0; k < 4; ++k) S[g][k] = (f32x2_t){0.f, 0.f};
;   }
;   const int orow = row_base + (part & (RG - 1)) * (NSW * 8) + wave * 8 + rowl;
;   char* const obase = dir == 0 ? (char*)(p.ws + OFF_YB) : (char*)(p.ws + OFF_OB);
;   const unsigned ostride = dir == 0 ? (unsigned)DM * 2u : 2048u;
;   const unsigned ooff0 = dir == 0 ? ((unsigned)tok0 * (unsigned)DM + 1024u + (unsigned)(64 * head + orow)) * 2u
;                                   : ((unsigned)tok0 * 1024u + (unsigned)(64 * head + orow)) * 2u;
.LBB0_1213:
	s_andn2_saveexec_b64 s[6:7], s[52:53]
	s_cbranch_execz .LBB0_1117
	s_setprio 2
	s_waitcnt vmcnt(3)
	v_lshlrev_b32_e32 v3, 5, v149
	v_lshlrev_b32_e32 v2, 3, v7
	v_and_b32_e32 v3, 32, v3
	s_waitcnt vmcnt(2)
	v_lshrrev_b32_e32 v0, 3, v149
	v_add_u32_e32 v3, v3, v2
	v_or_b32_e32 v3, v3, v0
	s_lshl_b32 s8, s90, 11
	s_mov_b64 s[4:5], -1
	s_and_b64 vcc, exec, s[12:13]
	s_cbranch_vccz .LBB0_1216
	s_add_i32 s4, s8, s65
	v_lshl_add_u32 v18, v3, 1, s4
	s_mov_b64 s[4:5], 0

; template <int RG>
; __device__ __forceinline__ void scan_waves16(const Params& p, float* lds, const int T, const int dir, const int wave, const int lane,
;                                            const size_t tok0, const int head, const int row_base) {
;     ...
;   const int rowl = lane >> 4, part = lane & 15, k0 = part * 4;
;   int rowi[RG]; f32x2_t S[RG][2];
; #pragma unroll
;   for (int g = 0; g < RG; ++g) { rowi[g] = row_base + g * 16 + wave * 4 + rowl; S[g][0] = S[g][1] = (f32x2_t){0.f, 0.f}; }
;   const int orow = row_base + (part & (RG - 1)) * 16 + wave * 4 + rowl;
;   char* const obase = dir == 0 ? (char*)(p.ws + OFF_YB) : (char*)(p.ws + OFF_OB);
;   const unsigned ostride = dir == 0 ? (unsigned)DM * 2u : 2048u;
;   const unsigned ooff0 = dir == 0 ? ((unsigned)tok0 * (unsigned)DM + 1024u + (unsigned)(64 * head + orow)) * 2u
;                                   : ((unsigned)tok0 * 1024u + (unsigned)(64 * head + orow)) * 2u;
;   const int nb = T / 16; int i3 = 0;
.LBB0_1346:
	s_andn2_saveexec_b64 s[4:5], s[46:47]
	s_cbranch_execz .LBB0_1353
	s_setprio 2
	s_brev_b32 s8, 48
	s_and_b64 s[6:7], s[0:1], exec
	s_cselect_b32 s6, s8, 0x1a900400
	s_add_u32 s6, s74, s6
	s_addc_u32 s7, s75, 0
	s_lshl_b32 s13, s59, 7
	s_add_i32 s14, s13, 0x800
	s_movk_i32 s11, 0x1000
	s_and_b64 s[8:9], s[0:1], exec
	s_cselect_b32 s11, s11, 0xfffff800
	s_sub_i32 s12, 12, s58
	s_waitcnt vmcnt(5)
	v_lshrrev_b32_e32 v0, 4, v148
	s_and_b64 s[8:9], s[0:1], exec
	v_lshl_or_b32 v0, s3, 4, v0
	s_cselect_b32 s8, s14, s13
	s_waitcnt vmcnt(4)
	v_and_b32_e32 v1, 15, v140
	s_waitcnt vmcnt(0)
	v_lshl_add_u32 v5, v6, 2, v0
	v_mov_b32_e32 v0, 0
	s_mov_b32 s10, 0
	v_lshlrev_b32_e32 v4, 2, v1
	v_lshl_add_u32 v6, v5, 1, s8
	v_lshl_add_u32 v7, v1, 4, 0
	v_cmp_eq_u32_e32 vcc, 0, v1
	s_mov_b32 s3, -2
	s_movk_i32 s13, 0xffe0
	s_movk_i32 s14, 0x401f
	s_movk_i32 s15, 0x7fff
	v_mov_b32_e32 v1, v0
	v_mov_b32_e32 v2, v0
	v_mov_b32_e32 v3, v0
	v_lshrrev_b32_e32 v8, 2, v4
	v_and_b32_e32 v9, 8, v4
	v_and_b32_e32 v13, 4, v4
	v_mul_lo_u32 v8, v8, s11
	s_branch .LBB0_1350

; template <int RG, int NSW>
; __device__ __forceinline__ void scan_job(const Params& p, float* lds, const size_t tok0, const int T, const int head,
;                                          const int dir, const int row_base, const int rk_sel) {
;     ...
;     if (wave < 4) scan_waves16<RG>(p, lds, T, dir, wave, lane, tok0, head, row_base);
;     else if (wave == 4) prep_waves<1, true, 0>(p, lds, T, dir, lane, tok0, head, 0, rk_sel);
;     else if (wave == 5) prep_waves<3, true, 1>(p, lds, T, dir, lane, tok0, head, 1, rk_sel);
;     else prep_waves<6, false, 0>(p, lds, T, dir, lane, tok0, head, 4 + (wave - 6) * 6, rk_sel);
.LBB0_1353:
	s_setprio 0
	s_or_b64 exec, exec, s[4:5]
